# G1 MFMA segment: software-pipelined LDS fragment reads (A fragments double-buffered, B fragment set per K-half) + priority toggle
# speedup vs baseline: 1.1493x; 1.0078x over previous
; __device__ __forceinline__ void gemm_core_big(const bf16_t* __restrict__ A, int lda, const bf16_t* __restrict__ Bt, int ldb,
;                                               int K, f32x4 (&acc)[8][4], char* smem) {
;     ...
;   for (int kt = 0; kt < nk; ++kt) {
;     __syncthreads();
; #pragma unroll
;     for (int i = 0; i < 8; ++i) *(u32x4*)(wA + 32 * i * LDS_STRIDE) = ra[i];
; #pragma unroll
;     for (int i = 0; i < 4; ++i) *(u32x4*)(wB + 32 * i * LDS_STRIDE) = rb[i];
;     __syncthreads();
;     {
;       const int k1 = min(kt + 1, nk - 1) << 6;
; #pragma unroll
;       for (int i = 0; i < 8; ++i) ra[i] = *(const u32x4*)(ap + (size_t)(32 * i) * lda + k1);
; #pragma unroll
;       for (int i = 0; i < 4; ++i) rb[i] = *(const u32x4*)(bp + (size_t)(32 * i) * ldb + k1);
;     }
; #pragma unroll
;     for (int ks = 0; ks < 2; ++ks) {
;       const int fo = ks ? fo1 : fo0;
;       bf16x8 bfr[4];
; #pragma unroll
;       for (int j = 0; j < 4; ++j) bfr[j] = *(const bf16x8*)(cB + j * 16 * LDS_STRIDE + fo);
; #pragma unroll
;       for (int i = 0; i < 8; ++i) {
;         const bf16x8 af = *(const bf16x8*)(cA + i * 16 * LDS_STRIDE + fo);
; #pragma unroll
;         for (int j = 0; j < 4; ++j)
;           acc[i][j] = __builtin_amdgcn_mfma_f32_16x16x32_bf16(bfr[j], af, acc[i][j], 0, 0, 0);
;       }
;     }
.LBB0_711:
	s_setprio 0
	v_add_co_u32_e32 v176, vcc, s1, v136
	global_load_dwordx4 v[144:147], v[136:137], off
	s_nop 0
	v_addc_co_u32_e32 v177, vcc, 0, v137, vcc
	v_add_co_u32_e32 v192, vcc, s15, v136
	s_mov_b32 s13, 0x40000
	s_nop 0
	v_addc_co_u32_e32 v193, vcc, 0, v137, vcc
	v_add_co_u32_e32 v196, vcc, s0, v136
	global_load_dwordx4 v[148:151], v[134:135], off
	s_nop 0
	v_addc_co_u32_e32 v197, vcc, 0, v137, vcc
	v_add_co_u32_e32 v136, vcc, s1, v134
	s_nop 1
	v_addc_co_u32_e32 v137, vcc, 0, v135, vcc
	v_add_co_u32_e32 v152, vcc, s15, v134
	s_nop 1
	v_addc_co_u32_e32 v153, vcc, 0, v135, vcc
	v_add_co_u32_e32 v156, vcc, s0, v134
	s_nop 1
	v_addc_co_u32_e32 v157, vcc, 0, v135, vcc
	v_add_co_u32_e32 v160, vcc, s13, v134
	s_mov_b32 s13, 0x50000
	s_nop 0
	v_addc_co_u32_e32 v161, vcc, 0, v135, vcc
	v_add_co_u32_e32 v164, vcc, s13, v134
	s_mov_b32 s13, 0x60000
	s_nop 0
	v_addc_co_u32_e32 v165, vcc, 0, v135, vcc
	v_add_co_u32_e32 v168, vcc, s13, v134
	s_mov_b32 s13, 0x70000
	s_nop 0
	v_addc_co_u32_e32 v169, vcc, 0, v135, vcc
	v_add_co_u32_e32 v172, vcc, s13, v134
	s_min_i32 s13, s26, 15
	s_nop 0
	v_addc_co_u32_e32 v173, vcc, 0, v135, vcc
	global_load_dwordx4 v[134:137], v[136:137], off
	s_nop 0
	global_load_dwordx4 v[152:155], v[152:153], off
	s_nop 0
	global_load_dwordx4 v[156:159], v[156:157], off
	s_nop 0
	global_load_dwordx4 v[160:163], v[160:161], off
	s_nop 0
	global_load_dwordx4 v[164:167], v[164:165], off
	s_nop 0
	global_load_dwordx4 v[168:171], v[168:169], off
	s_nop 0
	global_load_dwordx4 v[172:175], v[172:173], off
	s_nop 0
	global_load_dwordx4 v[188:191], v[176:177], off
	s_nop 0
	global_load_dwordx4 v[192:195], v[192:193], off
	s_nop 0
	global_load_dwordx4 v[196:199], v[196:197], off
	s_barrier
	s_add_i32 s26, s26, 1
	s_lshl_b32 s18, s13, 7
	s_cmp_lg_u32 s26, 17
	s_waitcnt vmcnt(10)
	ds_write_b128 v2, v[148:151]
	ds_write_b128 v2, v[144:147] offset:32768
	s_waitcnt vmcnt(9)
	ds_write_b128 v2, v[134:137] offset:4096
	s_waitcnt vmcnt(8)
	ds_write_b128 v2, v[152:155] offset:8192
	s_waitcnt vmcnt(7)
	ds_write_b128 v2, v[156:159] offset:12288
	s_waitcnt vmcnt(6)
	ds_write_b128 v2, v[160:163] offset:16384
	s_waitcnt vmcnt(5)
	ds_write_b128 v2, v[164:167] offset:20480
	s_waitcnt vmcnt(4)
	ds_write_b128 v2, v[168:171] offset:24576
	s_waitcnt vmcnt(3)
	ds_write_b128 v2, v[172:175] offset:28672
	s_waitcnt vmcnt(2)
	ds_write_b128 v2, v[188:191] offset:36864
	s_waitcnt vmcnt(1)
	ds_write_b128 v2, v[192:195] offset:40960
	s_waitcnt vmcnt(0)
	ds_write_b128 v2, v[196:199] offset:45056
	s_waitcnt lgkmcnt(0)
	s_barrier
	ds_read_b128 v[134:137], v140 offset:32768
	ds_read_b128 v[144:147], v140 offset:34816
	ds_read_b128 v[156:159], v140 offset:36864
	ds_read_b128 v[160:163], v140 offset:38912
	ds_read_b128 v[148:151], v141 offset:0
	ds_read_b128 v[152:155], v141 offset:2048
	ds_read_b128 v[216:219], v141 offset:4096
	ds_read_b128 v[220:223], v141 offset:6144
	s_setprio 1
	s_waitcnt lgkmcnt(3)
	v_mfma_f32_16x16x32_bf16 v[128:131], v[134:137], v[148:151], v[128:131]
	v_mfma_f32_16x16x32_bf16 v[124:127], v[144:147], v[148:151], v[124:127]
	v_mfma_f32_16x16x32_bf16 v[120:123], v[156:159], v[148:151], v[120:123]
	v_mfma_f32_16x16x32_bf16 v[116:119], v[160:163], v[148:151], v[116:119]
	s_waitcnt lgkmcnt(2)
	v_mfma_f32_16x16x32_bf16 v[112:115], v[134:137], v[152:155], v[112:115]
	v_mfma_f32_16x16x32_bf16 v[108:111], v[144:147], v[152:155], v[108:111]
	v_mfma_f32_16x16x32_bf16 v[104:107], v[156:159], v[152:155], v[104:107]
	v_mfma_f32_16x16x32_bf16 v[100:103], v[160:163], v[152:155], v[100:103]
	ds_read_b128 v[148:151], v141 offset:8192
	ds_read_b128 v[152:155], v141 offset:10240
	s_waitcnt lgkmcnt(3)
	v_mfma_f32_16x16x32_bf16 v[96:99], v[134:137], v[216:219], v[96:99]
	v_mfma_f32_16x16x32_bf16 v[92:95], v[144:147], v[216:219], v[92:95]
	v_mfma_f32_16x16x32_bf16 v[88:91], v[156:159], v[216:219], v[88:91]
	v_mfma_f32_16x16x32_bf16 v[84:87], v[160:163], v[216:219], v[84:87]
	s_waitcnt lgkmcnt(2)
	v_mfma_f32_16x16x32_bf16 v[80:83], v[134:137], v[220:223], v[80:83]
	v_mfma_f32_16x16x32_bf16 v[76:79], v[144:147], v[220:223], v[76:79]
	v_mfma_f32_16x16x32_bf16 v[72:75], v[156:159], v[220:223], v[72:75]
	v_mfma_f32_16x16x32_bf16 v[68:71], v[160:163], v[220:223], v[68:71]
	ds_read_b128 v[216:219], v141 offset:12288
	ds_read_b128 v[220:223], v141 offset:14336
	ds_read_b128 v[200:203], v142 offset:32768
	ds_read_b128 v[204:207], v142 offset:34816
	ds_read_b128 v[208:211], v142 offset:36864
	ds_read_b128 v[212:215], v142 offset:38912
	s_waitcnt lgkmcnt(7)
	v_mfma_f32_16x16x32_bf16 v[64:67], v[134:137], v[148:151], v[64:67]
	v_mfma_f32_16x16x32_bf16 v[60:63], v[144:147], v[148:151], v[60:63]
	v_mfma_f32_16x16x32_bf16 v[56:59], v[156:159], v[148:151], v[56:59]
	v_mfma_f32_16x16x32_bf16 v[52:55], v[160:163], v[148:151], v[52:55]
	s_waitcnt lgkmcnt(6)
	v_mfma_f32_16x16x32_bf16 v[48:51], v[134:137], v[152:155], v[48:51]
	v_mfma_f32_16x16x32_bf16 v[44:47], v[144:147], v[152:155], v[44:47]
	v_mfma_f32_16x16x32_bf16 v[40:43], v[156:159], v[152:155], v[40:43]
	v_mfma_f32_16x16x32_bf16 v[36:39], v[160:163], v[152:155], v[36:39]
	ds_read_b128 v[148:151], v143 offset:0
	ds_read_b128 v[152:155], v143 offset:2048
	s_waitcnt lgkmcnt(7)
	v_mfma_f32_16x16x32_bf16 v[32:35], v[134:137], v[216:219], v[32:35]
	v_mfma_f32_16x16x32_bf16 v[24:27], v[144:147], v[216:219], v[24:27]
	v_mfma_f32_16x16x32_bf16 v[20:23], v[156:159], v[216:219], v[20:23]
	v_mfma_f32_16x16x32_bf16 v[16:19], v[160:163], v[216:219], v[16:19]
	s_waitcnt lgkmcnt(6)
; __device__ __forceinline__ unsigned pack2(float a, float b) { return (unsigned)f2bf(a) | ((unsigned)f2bf(b) << 16); }
; __device__ __forceinline__ void gemm_core_big(const bf16_t* __restrict__ A, int lda, const bf16_t* __restrict__ Bt, int ldb,
;                                               int K, f32x4 (&acc)[8][4], char* smem) {
;     ...
; #pragma unroll
;     for (int ks = 0; ks < 2; ++ks) {
;       const int fo = ks ? fo1 : fo0;
;       bf16x8 bfr[4];
; #pragma unroll
;       for (int j = 0; j < 4; ++j) bfr[j] = *(const bf16x8*)(cB + j * 16 * LDS_STRIDE + fo);
; #pragma unroll
;       for (int i = 0; i < 8; ++i) {
;         const bf16x8 af = *(const bf16x8*)(cA + i * 16 * LDS_STRIDE + fo);
; #pragma unroll
;         for (int j = 0; j < 4; ++j)
;           acc[i][j] = __builtin_amdgcn_mfma_f32_16x16x32_bf16(bfr[j], af, acc[i][j], 0, 0, 0);
;       }
;     }
; __device__ __forceinline__ void phase_gemm_in(const Params& p, char* smem) {
;     ...
;     bf16_t* dst; int ldd, ncol0;
;     if (nt < PRE_W / 128) { dst = PRE; ldd = PRE_W; ncol0 = nt * 128; }
;     else { dst = POST; ldd = POST_W; ncol0 = (nt - PRE_W / 128) * 128; }
; #pragma unroll
;     for (int i = 0; i < 8; ++i) {
;       const int m = mt * 256 + wm * 128 + i * 16 + (lane & 15);
; #pragma unroll
;       for (int j = 0; j < 4; ++j) {
;         const int n = ncol0 + wn * 64 + j * 16 + (lane >> 4) * 4;
;         uint2 o;
;         o.x = pack2(acc[i][j][0], acc[i][j][1]);
;         o.y = pack2(acc[i][j][2], acc[i][j][3]);
;         *(uint2*)(dst + (size_t)m * ldd + n) = o;
;       }
;     }
	v_mfma_f32_16x16x32_bf16 v[12:15], v[134:137], v[220:223], v[12:15]
	v_mfma_f32_16x16x32_bf16 v[8:11], v[144:147], v[220:223], v[8:11]
	v_mfma_f32_16x16x32_bf16 v[4:7], v[156:159], v[220:223], v[4:7]
	v_mfma_f32_16x16x32_bf16 v[28:31], v[160:163], v[220:223], v[28:31]
	ds_read_b128 v[216:219], v143 offset:4096
	ds_read_b128 v[220:223], v143 offset:6144
	s_waitcnt lgkmcnt(3)
	v_mfma_f32_16x16x32_bf16 v[128:131], v[200:203], v[148:151], v[128:131]
	v_mfma_f32_16x16x32_bf16 v[124:127], v[204:207], v[148:151], v[124:127]
	v_mfma_f32_16x16x32_bf16 v[120:123], v[208:211], v[148:151], v[120:123]
	v_mfma_f32_16x16x32_bf16 v[116:119], v[212:215], v[148:151], v[116:119]
	s_waitcnt lgkmcnt(2)
	v_mfma_f32_16x16x32_bf16 v[112:115], v[200:203], v[152:155], v[112:115]
	v_mfma_f32_16x16x32_bf16 v[108:111], v[204:207], v[152:155], v[108:111]
	v_mfma_f32_16x16x32_bf16 v[104:107], v[208:211], v[152:155], v[104:107]
	v_mfma_f32_16x16x32_bf16 v[100:103], v[212:215], v[152:155], v[100:103]
	ds_read_b128 v[148:151], v143 offset:8192
	ds_read_b128 v[152:155], v143 offset:10240
	s_waitcnt lgkmcnt(3)
	v_mfma_f32_16x16x32_bf16 v[96:99], v[200:203], v[216:219], v[96:99]
	v_mfma_f32_16x16x32_bf16 v[92:95], v[204:207], v[216:219], v[92:95]
	v_mfma_f32_16x16x32_bf16 v[88:91], v[208:211], v[216:219], v[88:91]
	v_mfma_f32_16x16x32_bf16 v[84:87], v[212:215], v[216:219], v[84:87]
	s_waitcnt lgkmcnt(2)
	v_mfma_f32_16x16x32_bf16 v[80:83], v[200:203], v[220:223], v[80:83]
	v_mfma_f32_16x16x32_bf16 v[76:79], v[204:207], v[220:223], v[76:79]
	v_mfma_f32_16x16x32_bf16 v[72:75], v[208:211], v[220:223], v[72:75]
	v_mfma_f32_16x16x32_bf16 v[68:71], v[212:215], v[220:223], v[68:71]
	ds_read_b128 v[216:219], v143 offset:12288
	ds_read_b128 v[220:223], v143 offset:14336
	s_waitcnt lgkmcnt(3)
	v_mfma_f32_16x16x32_bf16 v[64:67], v[200:203], v[148:151], v[64:67]
	v_mfma_f32_16x16x32_bf16 v[60:63], v[204:207], v[148:151], v[60:63]
	v_mfma_f32_16x16x32_bf16 v[56:59], v[208:211], v[148:151], v[56:59]
	v_mfma_f32_16x16x32_bf16 v[52:55], v[212:215], v[148:151], v[52:55]
	s_waitcnt lgkmcnt(2)
	v_mfma_f32_16x16x32_bf16 v[48:51], v[200:203], v[152:155], v[48:51]
	v_mfma_f32_16x16x32_bf16 v[44:47], v[204:207], v[152:155], v[44:47]
	v_mfma_f32_16x16x32_bf16 v[40:43], v[208:211], v[152:155], v[40:43]
	v_mfma_f32_16x16x32_bf16 v[36:39], v[212:215], v[152:155], v[36:39]
	s_waitcnt lgkmcnt(1)
	v_mfma_f32_16x16x32_bf16 v[32:35], v[200:203], v[216:219], v[32:35]
	v_mfma_f32_16x16x32_bf16 v[24:27], v[204:207], v[216:219], v[24:27]
	v_mfma_f32_16x16x32_bf16 v[20:23], v[208:211], v[216:219], v[20:23]
	v_mfma_f32_16x16x32_bf16 v[16:19], v[212:215], v[216:219], v[16:19]
	s_waitcnt lgkmcnt(0)
	v_mfma_f32_16x16x32_bf16 v[12:15], v[200:203], v[220:223], v[12:15]
	v_mfma_f32_16x16x32_bf16 v[8:11], v[204:207], v[220:223], v[8:11]
	v_mfma_f32_16x16x32_bf16 v[4:7], v[208:211], v[220:223], v[4:7]
	v_mfma_f32_16x16x32_bf16 v[28:31], v[212:215], v[220:223], v[28:31]
	v_lshl_add_u64 v[134:135], v[0:1], 0, s[18:19]
	v_lshl_add_u64 v[136:137], v[132:133], 0, s[18:19]
	s_cbranch_scc1 .LBB0_711
	s_setprio 0
	s_lshl_b32 s13, s14, 7
	s_add_i32 s15, s13, 0xffffef00
	s_cmp_lt_i32 s14, 34
	s_mov_b32 s14, 0x4100000
	s_cselect_b32 s18, s14, 0xcb20000
	s_movk_i32 s0, 0x1200
	s_cselect_b32 s15, s13, s15
	v_and_b32_sdwa v134, v130, v183 dst_sel:DWORD dst_unused:UNUSED_PAD src0_sel:WORD_1 src1_sel:DWORD
	v_and_b32_sdwa v135, v128, v183 dst_sel:DWORD dst_unused:UNUSED_PAD src0_sel:WORD_1 src1_sel:DWORD
	s_cselect_b32 s14, 0x1100, s0
	v_lshl_add_u32 v2, s12, 8, v138
	s_add_u32 s12, s10, s18
	v_or_b32_e32 v0, s15, v139
	v_add3_u32 v128, v128, v135, s37
	v_add3_u32 v130, v130, v134, s37
	v_and_b32_sdwa v134, v131, v183 dst_sel:DWORD dst_unused:UNUSED_PAD src0_sel:WORD_1 src1_sel:DWORD
	v_and_b32_sdwa v135, v129, v183 dst_sel:DWORD dst_unused:UNUSED_PAD src0_sel:WORD_1 src1_sel:DWORD
	s_addc_u32 s13, s11, 0
	v_mad_i64_i32 v[132:133], s[26:27], s14, v2, 0
	v_ashrrev_i32_e32 v1, 31, v0
	v_add3_u32 v131, v131, v134, s37
	v_add3_u32 v129, v129, v135, s37
	v_lshl_add_u64 v[132:133], v[132:133], 1, s[12:13]
	v_lshlrev_b64 v[0:1], 1, v[0:1]
	v_and_b32_e32 v131, 0xffff0000, v131
	v_and_b32_e32 v134, 0xffff0000, v129
	v_lshl_add_u64 v[132:133], v[132:133], 0, v[0:1]
	v_or_b32_sdwa v129, v131, v130 dst_sel:DWORD dst_unused:UNUSED_PAD src0_sel:DWORD src1_sel:WORD_1
	v_or_b32_sdwa v128, v134, v128 dst_sel:DWORD dst_unused:UNUSED_PAD src0_sel:DWORD src1_sel:WORD_1
	global_store_dwordx2 v[132:133], v[128:129], off
	v_and_b32_sdwa v128, v126, v183 dst_sel:DWORD dst_unused:UNUSED_PAD src0_sel:WORD_1 src1_sel:DWORD
	v_and_b32_sdwa v129, v124, v183 dst_sel:DWORD dst_unused:UNUSED_PAD src0_sel:WORD_1 src1_sel:DWORD
	v_add3_u32 v124, v124, v129, s37
	v_add3_u32 v126, v126, v128, s37
	v_and_b32_sdwa v128, v127, v183 dst_sel:DWORD dst_unused:UNUSED_PAD src0_sel:WORD_1 src1_sel:DWORD
	v_and_b32_sdwa v129, v125, v183 dst_sel:DWORD dst_unused:UNUSED_PAD src0_sel:WORD_1 src1_sel:DWORD
	v_add3_u32 v127, v127, v128, s37
	v_add3_u32 v125, v125, v129, s37
	v_and_b32_e32 v127, 0xffff0000, v127
	v_and_b32_e32 v128, 0xffff0000, v125
	v_or_b32_sdwa v125, v127, v126 dst_sel:DWORD dst_unused:UNUSED_PAD src0_sel:DWORD src1_sel:WORD_1
	v_or_b32_sdwa v124, v128, v124 dst_sel:DWORD dst_unused:UNUSED_PAD src0_sel:DWORD src1_sel:WORD_1
	global_store_dwordx2 v[132:133], v[124:125], off offset:32
	v_and_b32_sdwa v124, v122, v183 dst_sel:DWORD dst_unused:UNUSED_PAD src0_sel:WORD_1 src1_sel:DWORD
	v_and_b32_sdwa v125, v120, v183 dst_sel:DWORD dst_unused:UNUSED_PAD src0_sel:WORD_1 src1_sel:DWORD
	v_add3_u32 v120, v120, v125, s37
	v_add3_u32 v122, v122, v124, s37
; __device__ __forceinline__ unsigned pack2(float a, float b) { return (unsigned)f2bf(a) | ((unsigned)f2bf(b) << 16); }
; __device__ __forceinline__ void phase_gemm_in(const Params& p, char* smem) {
;     ...
; #pragma unroll
;     for (int i = 0; i < 8; ++i) {
;       const int m = mt * 256 + wm * 128 + i * 16 + (lane & 15);
; #pragma unroll
;       for (int j = 0; j < 4; ++j) {
;         const int n = ncol0 + wn * 64 + j * 16 + (lane >> 4) * 4;
;         uint2 o;
;         o.x = pack2(acc[i][j][0], acc[i][j][1]);
;         o.y = pack2(acc[i][j][2], acc[i][j][3]);
;         *(uint2*)(dst + (size_t)m * ldd + n) = o;
;       }
;     }
	v_and_b32_sdwa v124, v123, v183 dst_sel:DWORD dst_unused:UNUSED_PAD src0_sel:WORD_1 src1_sel:DWORD
	v_and_b32_sdwa v125, v121, v183 dst_sel:DWORD dst_unused:UNUSED_PAD src0_sel:WORD_1 src1_sel:DWORD
	v_add3_u32 v123, v123, v124, s37
	v_add3_u32 v121, v121, v125, s37
	v_and_b32_e32 v123, 0xffff0000, v123
	v_and_b32_e32 v124, 0xffff0000, v121
	v_or_b32_sdwa v121, v123, v122 dst_sel:DWORD dst_unused:UNUSED_PAD src0_sel:DWORD src1_sel:WORD_1
	v_or_b32_sdwa v120, v124, v120 dst_sel:DWORD dst_unused:UNUSED_PAD src0_sel:DWORD src1_sel:WORD_1
	global_store_dwordx2 v[132:133], v[120:121], off offset:64
	v_and_b32_sdwa v120, v118, v183 dst_sel:DWORD dst_unused:UNUSED_PAD src0_sel:WORD_1 src1_sel:DWORD
	v_and_b32_sdwa v121, v116, v183 dst_sel:DWORD dst_unused:UNUSED_PAD src0_sel:WORD_1 src1_sel:DWORD
	v_add3_u32 v116, v116, v121, s37
	v_add3_u32 v118, v118, v120, s37
	v_and_b32_sdwa v120, v119, v183 dst_sel:DWORD dst_unused:UNUSED_PAD src0_sel:WORD_1 src1_sel:DWORD
	v_and_b32_sdwa v121, v117, v183 dst_sel:DWORD dst_unused:UNUSED_PAD src0_sel:WORD_1 src1_sel:DWORD
	v_add3_u32 v119, v119, v120, s37
	v_add3_u32 v117, v117, v121, s37
	v_and_b32_e32 v119, 0xffff0000, v119
	v_and_b32_e32 v120, 0xffff0000, v117
	v_or_b32_sdwa v117, v119, v118 dst_sel:DWORD dst_unused:UNUSED_PAD src0_sel:DWORD src1_sel:WORD_1
	v_or_b32_sdwa v116, v120, v116 dst_sel:DWORD dst_unused:UNUSED_PAD src0_sel:DWORD src1_sel:WORD_1
	v_and_b32_sdwa v118, v114, v183 dst_sel:DWORD dst_unused:UNUSED_PAD src0_sel:WORD_1 src1_sel:DWORD
	v_and_b32_sdwa v119, v112, v183 dst_sel:DWORD dst_unused:UNUSED_PAD src0_sel:WORD_1 src1_sel:DWORD
	global_store_dwordx2 v[132:133], v[116:117], off offset:96
	v_or_b32_e32 v116, 16, v2
	v_add3_u32 v112, v112, v119, s37
	v_add3_u32 v114, v114, v118, s37
	v_and_b32_sdwa v118, v115, v183 dst_sel:DWORD dst_unused:UNUSED_PAD src0_sel:WORD_1 src1_sel:DWORD
	v_and_b32_sdwa v119, v113, v183 dst_sel:DWORD dst_unused:UNUSED_PAD src0_sel:WORD_1 src1_sel:DWORD
	v_mad_i64_i32 v[116:117], s[26:27], s14, v116, 0
	v_add3_u32 v115, v115, v118, s37
	v_add3_u32 v113, v113, v119, s37
	v_lshl_add_u64 v[116:117], v[116:117], 1, s[12:13]
	v_and_b32_e32 v115, 0xffff0000, v115
	v_and_b32_e32 v118, 0xffff0000, v113
	v_lshl_add_u64 v[116:117], v[116:117], 0, v[0:1]
	v_or_b32_sdwa v113, v115, v114 dst_sel:DWORD dst_unused:UNUSED_PAD src0_sel:DWORD src1_sel:WORD_1
	v_or_b32_sdwa v112, v118, v112 dst_sel:DWORD dst_unused:UNUSED_PAD src0_sel:DWORD src1_sel:WORD_1
	global_store_dwordx2 v[116:117], v[112:113], off
	v_and_b32_sdwa v112, v110, v183 dst_sel:DWORD dst_unused:UNUSED_PAD src0_sel:WORD_1 src1_sel:DWORD
	v_and_b32_sdwa v113, v108, v183 dst_sel:DWORD dst_unused:UNUSED_PAD src0_sel:WORD_1 src1_sel:DWORD
	v_add3_u32 v108, v108, v113, s37
	v_add3_u32 v110, v110, v112, s37
	v_and_b32_sdwa v112, v111, v183 dst_sel:DWORD dst_unused:UNUSED_PAD src0_sel:WORD_1 src1_sel:DWORD
	v_and_b32_sdwa v113, v109, v183 dst_sel:DWORD dst_unused:UNUSED_PAD src0_sel:WORD_1 src1_sel:DWORD
	v_add3_u32 v111, v111, v112, s37
	v_add3_u32 v109, v109, v113, s37
	v_and_b32_e32 v111, 0xffff0000, v111
	v_and_b32_e32 v112, 0xffff0000, v109
	v_or_b32_sdwa v109, v111, v110 dst_sel:DWORD dst_unused:UNUSED_PAD src0_sel:DWORD src1_sel:WORD_1
	v_or_b32_sdwa v108, v112, v108 dst_sel:DWORD dst_unused:UNUSED_PAD src0_sel:DWORD src1_sel:WORD_1
	global_store_dwordx2 v[116:117], v[108:109], off offset:32
	v_and_b32_sdwa v108, v106, v183 dst_sel:DWORD dst_unused:UNUSED_PAD src0_sel:WORD_1 src1_sel:DWORD
	v_and_b32_sdwa v109, v104, v183 dst_sel:DWORD dst_unused:UNUSED_PAD src0_sel:WORD_1 src1_sel:DWORD
	v_add3_u32 v104, v104, v109, s37
	v_add3_u32 v106, v106, v108, s37
	v_and_b32_sdwa v108, v107, v183 dst_sel:DWORD dst_unused:UNUSED_PAD src0_sel:WORD_1 src1_sel:DWORD
	v_and_b32_sdwa v109, v105, v183 dst_sel:DWORD dst_unused:UNUSED_PAD src0_sel:WORD_1 src1_sel:DWORD
	v_add3_u32 v107, v107, v108, s37
	v_add3_u32 v105, v105, v109, s37
	v_and_b32_e32 v107, 0xffff0000, v107
	v_and_b32_e32 v108, 0xffff0000, v105
	v_or_b32_sdwa v105, v107, v106 dst_sel:DWORD dst_unused:UNUSED_PAD src0_sel:DWORD src1_sel:WORD_1
	v_or_b32_sdwa v104, v108, v104 dst_sel:DWORD dst_unused:UNUSED_PAD src0_sel:DWORD src1_sel:WORD_1
	global_store_dwordx2 v[116:117], v[104:105], off offset:64
	v_and_b32_sdwa v104, v102, v183 dst_sel:DWORD dst_unused:UNUSED_PAD src0_sel:WORD_1 src1_sel:DWORD
	v_and_b32_sdwa v105, v100, v183 dst_sel:DWORD dst_unused:UNUSED_PAD src0_sel:WORD_1 src1_sel:DWORD
	v_add3_u32 v100, v100, v105, s37
	v_add3_u32 v102, v102, v104, s37
	v_and_b32_sdwa v104, v103, v183 dst_sel:DWORD dst_unused:UNUSED_PAD src0_sel:WORD_1 src1_sel:DWORD
	v_and_b32_sdwa v105, v101, v183 dst_sel:DWORD dst_unused:UNUSED_PAD src0_sel:WORD_1 src1_sel:DWORD
	v_add3_u32 v103, v103, v104, s37
	v_add3_u32 v101, v101, v105, s37
	v_and_b32_e32 v103, 0xffff0000, v103
	v_and_b32_e32 v104, 0xffff0000, v101
	v_or_b32_sdwa v101, v103, v102 dst_sel:DWORD dst_unused:UNUSED_PAD src0_sel:DWORD src1_sel:WORD_1
	v_or_b32_sdwa v100, v104, v100 dst_sel:DWORD dst_unused:UNUSED_PAD src0_sel:DWORD src1_sel:WORD_1
	v_and_b32_sdwa v102, v98, v183 dst_sel:DWORD dst_unused:UNUSED_PAD src0_sel:WORD_1 src1_sel:DWORD
	v_and_b32_sdwa v103, v96, v183 dst_sel:DWORD dst_unused:UNUSED_PAD src0_sel:WORD_1 src1_sel:DWORD
	global_store_dwordx2 v[116:117], v[100:101], off offset:96
	v_or_b32_e32 v100, 32, v2
	v_add3_u32 v96, v96, v103, s37
	v_add3_u32 v98, v98, v102, s37
	v_and_b32_sdwa v102, v99, v183 dst_sel:DWORD dst_unused:UNUSED_PAD src0_sel:WORD_1 src1_sel:DWORD
	v_and_b32_sdwa v103, v97, v183 dst_sel:DWORD dst_unused:UNUSED_PAD src0_sel:WORD_1 src1_sel:DWORD
	v_mad_i64_i32 v[100:101], s[26:27], s14, v100, 0
; __device__ __forceinline__ unsigned pack2(float a, float b) { return (unsigned)f2bf(a) | ((unsigned)f2bf(b) << 16); }
; __device__ __forceinline__ void phase_gemm_in(const Params& p, char* smem) {
;     ...
; #pragma unroll
;     for (int i = 0; i < 8; ++i) {
;       const int m = mt * 256 + wm * 128 + i * 16 + (lane & 15);
; #pragma unroll
;       for (int j = 0; j < 4; ++j) {
;         const int n = ncol0 + wn * 64 + j * 16 + (lane >> 4) * 4;
;         uint2 o;
;         o.x = pack2(acc[i][j][0], acc[i][j][1]);
;         o.y = pack2(acc[i][j][2], acc[i][j][3]);
;         *(uint2*)(dst + (size_t)m * ldd + n) = o;
;       }
;     }
	v_add3_u32 v99, v99, v102, s37
	v_add3_u32 v97, v97, v103, s37
	v_lshl_add_u64 v[100:101], v[100:101], 1, s[12:13]
	v_and_b32_e32 v99, 0xffff0000, v99
	v_and_b32_e32 v102, 0xffff0000, v97
	v_lshl_add_u64 v[100:101], v[100:101], 0, v[0:1]
	v_or_b32_sdwa v97, v99, v98 dst_sel:DWORD dst_unused:UNUSED_PAD src0_sel:DWORD src1_sel:WORD_1
	v_or_b32_sdwa v96, v102, v96 dst_sel:DWORD dst_unused:UNUSED_PAD src0_sel:DWORD src1_sel:WORD_1
	global_store_dwordx2 v[100:101], v[96:97], off
	v_and_b32_sdwa v96, v94, v183 dst_sel:DWORD dst_unused:UNUSED_PAD src0_sel:WORD_1 src1_sel:DWORD
	v_and_b32_sdwa v97, v92, v183 dst_sel:DWORD dst_unused:UNUSED_PAD src0_sel:WORD_1 src1_sel:DWORD
	v_add3_u32 v92, v92, v97, s37
	v_add3_u32 v94, v94, v96, s37
	v_and_b32_sdwa v96, v95, v183 dst_sel:DWORD dst_unused:UNUSED_PAD src0_sel:WORD_1 src1_sel:DWORD
	v_and_b32_sdwa v97, v93, v183 dst_sel:DWORD dst_unused:UNUSED_PAD src0_sel:WORD_1 src1_sel:DWORD
	v_add3_u32 v95, v95, v96, s37
	v_add3_u32 v93, v93, v97, s37
	v_and_b32_e32 v95, 0xffff0000, v95
	v_and_b32_e32 v96, 0xffff0000, v93
	v_or_b32_sdwa v93, v95, v94 dst_sel:DWORD dst_unused:UNUSED_PAD src0_sel:DWORD src1_sel:WORD_1
	v_or_b32_sdwa v92, v96, v92 dst_sel:DWORD dst_unused:UNUSED_PAD src0_sel:DWORD src1_sel:WORD_1
	global_store_dwordx2 v[100:101], v[92:93], off offset:32
	v_and_b32_sdwa v92, v90, v183 dst_sel:DWORD dst_unused:UNUSED_PAD src0_sel:WORD_1 src1_sel:DWORD
	v_and_b32_sdwa v93, v88, v183 dst_sel:DWORD dst_unused:UNUSED_PAD src0_sel:WORD_1 src1_sel:DWORD
	v_add3_u32 v88, v88, v93, s37
	v_add3_u32 v90, v90, v92, s37
	v_and_b32_sdwa v92, v91, v183 dst_sel:DWORD dst_unused:UNUSED_PAD src0_sel:WORD_1 src1_sel:DWORD
	v_and_b32_sdwa v93, v89, v183 dst_sel:DWORD dst_unused:UNUSED_PAD src0_sel:WORD_1 src1_sel:DWORD
	v_add3_u32 v91, v91, v92, s37
	v_add3_u32 v89, v89, v93, s37
	v_and_b32_e32 v91, 0xffff0000, v91
	v_and_b32_e32 v92, 0xffff0000, v89
	v_or_b32_sdwa v89, v91, v90 dst_sel:DWORD dst_unused:UNUSED_PAD src0_sel:DWORD src1_sel:WORD_1
	v_or_b32_sdwa v88, v92, v88 dst_sel:DWORD dst_unused:UNUSED_PAD src0_sel:DWORD src1_sel:WORD_1
	global_store_dwordx2 v[100:101], v[88:89], off offset:64
	v_and_b32_sdwa v88, v86, v183 dst_sel:DWORD dst_unused:UNUSED_PAD src0_sel:WORD_1 src1_sel:DWORD
	v_and_b32_sdwa v89, v84, v183 dst_sel:DWORD dst_unused:UNUSED_PAD src0_sel:WORD_1 src1_sel:DWORD
	v_add3_u32 v84, v84, v89, s37
	v_add3_u32 v86, v86, v88, s37
	v_and_b32_sdwa v88, v87, v183 dst_sel:DWORD dst_unused:UNUSED_PAD src0_sel:WORD_1 src1_sel:DWORD
	v_and_b32_sdwa v89, v85, v183 dst_sel:DWORD dst_unused:UNUSED_PAD src0_sel:WORD_1 src1_sel:DWORD
	v_add3_u32 v87, v87, v88, s37
	v_add3_u32 v85, v85, v89, s37
	v_and_b32_e32 v87, 0xffff0000, v87
	v_and_b32_e32 v88, 0xffff0000, v85
	v_or_b32_sdwa v85, v87, v86 dst_sel:DWORD dst_unused:UNUSED_PAD src0_sel:DWORD src1_sel:WORD_1
	v_or_b32_sdwa v84, v88, v84 dst_sel:DWORD dst_unused:UNUSED_PAD src0_sel:DWORD src1_sel:WORD_1
	v_and_b32_sdwa v86, v82, v183 dst_sel:DWORD dst_unused:UNUSED_PAD src0_sel:WORD_1 src1_sel:DWORD
	v_and_b32_sdwa v87, v80, v183 dst_sel:DWORD dst_unused:UNUSED_PAD src0_sel:WORD_1 src1_sel:DWORD
	global_store_dwordx2 v[100:101], v[84:85], off offset:96
	v_or_b32_e32 v84, 48, v2
	v_add3_u32 v80, v80, v87, s37
	v_add3_u32 v82, v82, v86, s37
	v_and_b32_sdwa v86, v83, v183 dst_sel:DWORD dst_unused:UNUSED_PAD src0_sel:WORD_1 src1_sel:DWORD
	v_and_b32_sdwa v87, v81, v183 dst_sel:DWORD dst_unused:UNUSED_PAD src0_sel:WORD_1 src1_sel:DWORD
	v_mad_i64_i32 v[84:85], s[26:27], s14, v84, 0
	v_add3_u32 v83, v83, v86, s37
	v_add3_u32 v81, v81, v87, s37
	v_lshl_add_u64 v[84:85], v[84:85], 1, s[12:13]
	v_and_b32_e32 v83, 0xffff0000, v83
	v_and_b32_e32 v86, 0xffff0000, v81
	v_lshl_add_u64 v[84:85], v[84:85], 0, v[0:1]
	v_or_b32_sdwa v81, v83, v82 dst_sel:DWORD dst_unused:UNUSED_PAD src0_sel:DWORD src1_sel:WORD_1
	v_or_b32_sdwa v80, v86, v80 dst_sel:DWORD dst_unused:UNUSED_PAD src0_sel:DWORD src1_sel:WORD_1
	global_store_dwordx2 v[84:85], v[80:81], off
	v_and_b32_sdwa v80, v78, v183 dst_sel:DWORD dst_unused:UNUSED_PAD src0_sel:WORD_1 src1_sel:DWORD
	v_and_b32_sdwa v81, v76, v183 dst_sel:DWORD dst_unused:UNUSED_PAD src0_sel:WORD_1 src1_sel:DWORD
	v_add3_u32 v76, v76, v81, s37
	v_add3_u32 v78, v78, v80, s37
	v_and_b32_sdwa v80, v79, v183 dst_sel:DWORD dst_unused:UNUSED_PAD src0_sel:WORD_1 src1_sel:DWORD
	v_and_b32_sdwa v81, v77, v183 dst_sel:DWORD dst_unused:UNUSED_PAD src0_sel:WORD_1 src1_sel:DWORD
	v_add3_u32 v79, v79, v80, s37
	v_add3_u32 v77, v77, v81, s37
	v_and_b32_e32 v79, 0xffff0000, v79
	v_and_b32_e32 v80, 0xffff0000, v77
	v_or_b32_sdwa v77, v79, v78 dst_sel:DWORD dst_unused:UNUSED_PAD src0_sel:DWORD src1_sel:WORD_1
	v_or_b32_sdwa v76, v80, v76 dst_sel:DWORD dst_unused:UNUSED_PAD src0_sel:DWORD src1_sel:WORD_1
	global_store_dwordx2 v[84:85], v[76:77], off offset:32
	v_and_b32_sdwa v76, v74, v183 dst_sel:DWORD dst_unused:UNUSED_PAD src0_sel:WORD_1 src1_sel:DWORD
	v_and_b32_sdwa v77, v72, v183 dst_sel:DWORD dst_unused:UNUSED_PAD src0_sel:WORD_1 src1_sel:DWORD
	v_add3_u32 v72, v72, v77, s37
	v_add3_u32 v74, v74, v76, s37
	v_and_b32_sdwa v76, v75, v183 dst_sel:DWORD dst_unused:UNUSED_PAD src0_sel:WORD_1 src1_sel:DWORD
	v_and_b32_sdwa v77, v73, v183 dst_sel:DWORD dst_unused:UNUSED_PAD src0_sel:WORD_1 src1_sel:DWORD
	v_add3_u32 v75, v75, v76, s37
	v_add3_u32 v73, v73, v77, s37
	v_and_b32_e32 v75, 0xffff0000, v75
	v_and_b32_e32 v76, 0xffff0000, v73
	v_or_b32_sdwa v73, v75, v74 dst_sel:DWORD dst_unused:UNUSED_PAD src0_sel:DWORD src1_sel:WORD_1
	v_or_b32_sdwa v72, v76, v72 dst_sel:DWORD dst_unused:UNUSED_PAD src0_sel:DWORD src1_sel:WORD_1
	global_store_dwordx2 v[84:85], v[72:73], off offset:64
; __device__ __forceinline__ unsigned pack2(float a, float b) { return (unsigned)f2bf(a) | ((unsigned)f2bf(b) << 16); }
; __device__ __forceinline__ void phase_gemm_in(const Params& p, char* smem) {
;     ...
; #pragma unroll
;     for (int i = 0; i < 8; ++i) {
;       const int m = mt * 256 + wm * 128 + i * 16 + (lane & 15);
; #pragma unroll
;       for (int j = 0; j < 4; ++j) {
;         const int n = ncol0 + wn * 64 + j * 16 + (lane >> 4) * 4;
;         uint2 o;
;         o.x = pack2(acc[i][j][0], acc[i][j][1]);
;         o.y = pack2(acc[i][j][2], acc[i][j][3]);
;         *(uint2*)(dst + (size_t)m * ldd + n) = o;
;       }
;     }
	v_and_b32_sdwa v72, v70, v183 dst_sel:DWORD dst_unused:UNUSED_PAD src0_sel:WORD_1 src1_sel:DWORD
	v_and_b32_sdwa v73, v68, v183 dst_sel:DWORD dst_unused:UNUSED_PAD src0_sel:WORD_1 src1_sel:DWORD
	v_add3_u32 v68, v68, v73, s37
	v_add3_u32 v70, v70, v72, s37
	v_and_b32_sdwa v72, v71, v183 dst_sel:DWORD dst_unused:UNUSED_PAD src0_sel:WORD_1 src1_sel:DWORD
	v_and_b32_sdwa v73, v69, v183 dst_sel:DWORD dst_unused:UNUSED_PAD src0_sel:WORD_1 src1_sel:DWORD
	v_add3_u32 v71, v71, v72, s37
	v_add3_u32 v69, v69, v73, s37
	v_and_b32_e32 v71, 0xffff0000, v71
	v_and_b32_e32 v72, 0xffff0000, v69
	v_or_b32_sdwa v69, v71, v70 dst_sel:DWORD dst_unused:UNUSED_PAD src0_sel:DWORD src1_sel:WORD_1
	v_or_b32_sdwa v68, v72, v68 dst_sel:DWORD dst_unused:UNUSED_PAD src0_sel:DWORD src1_sel:WORD_1
	v_and_b32_sdwa v70, v66, v183 dst_sel:DWORD dst_unused:UNUSED_PAD src0_sel:WORD_1 src1_sel:DWORD
	v_and_b32_sdwa v71, v64, v183 dst_sel:DWORD dst_unused:UNUSED_PAD src0_sel:WORD_1 src1_sel:DWORD
	global_store_dwordx2 v[84:85], v[68:69], off offset:96
	v_or_b32_e32 v68, 64, v2
	v_add3_u32 v64, v64, v71, s37
	v_add3_u32 v66, v66, v70, s37
	v_and_b32_sdwa v70, v67, v183 dst_sel:DWORD dst_unused:UNUSED_PAD src0_sel:WORD_1 src1_sel:DWORD
	v_and_b32_sdwa v71, v65, v183 dst_sel:DWORD dst_unused:UNUSED_PAD src0_sel:WORD_1 src1_sel:DWORD
	v_mad_i64_i32 v[68:69], s[26:27], s14, v68, 0
	v_add3_u32 v67, v67, v70, s37
	v_add3_u32 v65, v65, v71, s37
	v_lshl_add_u64 v[68:69], v[68:69], 1, s[12:13]
	v_and_b32_e32 v67, 0xffff0000, v67
	v_and_b32_e32 v70, 0xffff0000, v65
	v_lshl_add_u64 v[68:69], v[68:69], 0, v[0:1]
	v_or_b32_sdwa v65, v67, v66 dst_sel:DWORD dst_unused:UNUSED_PAD src0_sel:DWORD src1_sel:WORD_1
	v_or_b32_sdwa v64, v70, v64 dst_sel:DWORD dst_unused:UNUSED_PAD src0_sel:DWORD src1_sel:WORD_1
	global_store_dwordx2 v[68:69], v[64:65], off
	v_and_b32_sdwa v64, v62, v183 dst_sel:DWORD dst_unused:UNUSED_PAD src0_sel:WORD_1 src1_sel:DWORD
	v_and_b32_sdwa v65, v60, v183 dst_sel:DWORD dst_unused:UNUSED_PAD src0_sel:WORD_1 src1_sel:DWORD
	v_add3_u32 v60, v60, v65, s37
	v_add3_u32 v62, v62, v64, s37
	v_and_b32_sdwa v64, v63, v183 dst_sel:DWORD dst_unused:UNUSED_PAD src0_sel:WORD_1 src1_sel:DWORD
	v_and_b32_sdwa v65, v61, v183 dst_sel:DWORD dst_unused:UNUSED_PAD src0_sel:WORD_1 src1_sel:DWORD
	v_add3_u32 v63, v63, v64, s37
	v_add3_u32 v61, v61, v65, s37
	v_and_b32_e32 v63, 0xffff0000, v63
	v_and_b32_e32 v64, 0xffff0000, v61
	v_or_b32_sdwa v61, v63, v62 dst_sel:DWORD dst_unused:UNUSED_PAD src0_sel:DWORD src1_sel:WORD_1
	v_or_b32_sdwa v60, v64, v60 dst_sel:DWORD dst_unused:UNUSED_PAD src0_sel:DWORD src1_sel:WORD_1
	global_store_dwordx2 v[68:69], v[60:61], off offset:32
	v_and_b32_sdwa v60, v58, v183 dst_sel:DWORD dst_unused:UNUSED_PAD src0_sel:WORD_1 src1_sel:DWORD
	v_and_b32_sdwa v61, v56, v183 dst_sel:DWORD dst_unused:UNUSED_PAD src0_sel:WORD_1 src1_sel:DWORD
	v_add3_u32 v56, v56, v61, s37
	v_add3_u32 v58, v58, v60, s37
	v_and_b32_sdwa v60, v59, v183 dst_sel:DWORD dst_unused:UNUSED_PAD src0_sel:WORD_1 src1_sel:DWORD
	v_and_b32_sdwa v61, v57, v183 dst_sel:DWORD dst_unused:UNUSED_PAD src0_sel:WORD_1 src1_sel:DWORD
	v_add3_u32 v59, v59, v60, s37
	v_add3_u32 v57, v57, v61, s37
	v_and_b32_e32 v59, 0xffff0000, v59
	v_and_b32_e32 v60, 0xffff0000, v57
	v_or_b32_sdwa v57, v59, v58 dst_sel:DWORD dst_unused:UNUSED_PAD src0_sel:DWORD src1_sel:WORD_1
	v_or_b32_sdwa v56, v60, v56 dst_sel:DWORD dst_unused:UNUSED_PAD src0_sel:DWORD src1_sel:WORD_1
	global_store_dwordx2 v[68:69], v[56:57], off offset:64
	v_and_b32_sdwa v56, v54, v183 dst_sel:DWORD dst_unused:UNUSED_PAD src0_sel:WORD_1 src1_sel:DWORD
	v_and_b32_sdwa v57, v52, v183 dst_sel:DWORD dst_unused:UNUSED_PAD src0_sel:WORD_1 src1_sel:DWORD
	v_add3_u32 v52, v52, v57, s37
	v_add3_u32 v54, v54, v56, s37
	v_and_b32_sdwa v56, v55, v183 dst_sel:DWORD dst_unused:UNUSED_PAD src0_sel:WORD_1 src1_sel:DWORD
	v_and_b32_sdwa v57, v53, v183 dst_sel:DWORD dst_unused:UNUSED_PAD src0_sel:WORD_1 src1_sel:DWORD
	v_add3_u32 v55, v55, v56, s37
	v_add3_u32 v53, v53, v57, s37
	v_and_b32_e32 v55, 0xffff0000, v55
	v_and_b32_e32 v56, 0xffff0000, v53
	v_or_b32_sdwa v53, v55, v54 dst_sel:DWORD dst_unused:UNUSED_PAD src0_sel:DWORD src1_sel:WORD_1
	v_or_b32_sdwa v52, v56, v52 dst_sel:DWORD dst_unused:UNUSED_PAD src0_sel:DWORD src1_sel:WORD_1
	v_and_b32_sdwa v54, v50, v183 dst_sel:DWORD dst_unused:UNUSED_PAD src0_sel:WORD_1 src1_sel:DWORD
	v_and_b32_sdwa v55, v48, v183 dst_sel:DWORD dst_unused:UNUSED_PAD src0_sel:WORD_1 src1_sel:DWORD
	global_store_dwordx2 v[68:69], v[52:53], off offset:96
	v_or_b32_e32 v52, 0x50, v2
	v_add3_u32 v48, v48, v55, s37
	v_add3_u32 v50, v50, v54, s37
	v_and_b32_sdwa v54, v51, v183 dst_sel:DWORD dst_unused:UNUSED_PAD src0_sel:WORD_1 src1_sel:DWORD
	v_and_b32_sdwa v55, v49, v183 dst_sel:DWORD dst_unused:UNUSED_PAD src0_sel:WORD_1 src1_sel:DWORD
	v_mad_i64_i32 v[52:53], s[26:27], s14, v52, 0
	v_add3_u32 v51, v51, v54, s37
	v_add3_u32 v49, v49, v55, s37
	v_lshl_add_u64 v[52:53], v[52:53], 1, s[12:13]
	v_and_b32_e32 v51, 0xffff0000, v51
	v_and_b32_e32 v54, 0xffff0000, v49
	v_lshl_add_u64 v[52:53], v[52:53], 0, v[0:1]
	v_or_b32_sdwa v49, v51, v50 dst_sel:DWORD dst_unused:UNUSED_PAD src0_sel:DWORD src1_sel:WORD_1
	v_or_b32_sdwa v48, v54, v48 dst_sel:DWORD dst_unused:UNUSED_PAD src0_sel:DWORD src1_sel:WORD_1
	global_store_dwordx2 v[52:53], v[48:49], off
	v_and_b32_sdwa v48, v46, v183 dst_sel:DWORD dst_unused:UNUSED_PAD src0_sel:WORD_1 src1_sel:DWORD
	v_and_b32_sdwa v49, v44, v183 dst_sel:DWORD dst_unused:UNUSED_PAD src0_sel:WORD_1 src1_sel:DWORD
	v_add3_u32 v44, v44, v49, s37
	v_add3_u32 v46, v46, v48, s37
	v_and_b32_sdwa v48, v47, v183 dst_sel:DWORD dst_unused:UNUSED_PAD src0_sel:WORD_1 src1_sel:DWORD
; __device__ __forceinline__ unsigned pack2(float a, float b) { return (unsigned)f2bf(a) | ((unsigned)f2bf(b) << 16); }
; __device__ __forceinline__ void phase_gemm_in(const Params& p, char* smem) {
;     ...
; #pragma unroll
;     for (int i = 0; i < 8; ++i) {
;       const int m = mt * 256 + wm * 128 + i * 16 + (lane & 15);
; #pragma unroll
;       for (int j = 0; j < 4; ++j) {
;         const int n = ncol0 + wn * 64 + j * 16 + (lane >> 4) * 4;
;         uint2 o;
;         o.x = pack2(acc[i][j][0], acc[i][j][1]);
;         o.y = pack2(acc[i][j][2], acc[i][j][3]);
;         *(uint2*)(dst + (size_t)m * ldd + n) = o;
;       }
;     }
	v_and_b32_sdwa v49, v45, v183 dst_sel:DWORD dst_unused:UNUSED_PAD src0_sel:WORD_1 src1_sel:DWORD
	v_add3_u32 v47, v47, v48, s37
	v_add3_u32 v45, v45, v49, s37
	v_and_b32_e32 v47, 0xffff0000, v47
	v_and_b32_e32 v48, 0xffff0000, v45
	v_or_b32_sdwa v45, v47, v46 dst_sel:DWORD dst_unused:UNUSED_PAD src0_sel:DWORD src1_sel:WORD_1
	v_or_b32_sdwa v44, v48, v44 dst_sel:DWORD dst_unused:UNUSED_PAD src0_sel:DWORD src1_sel:WORD_1
	global_store_dwordx2 v[52:53], v[44:45], off offset:32
	v_and_b32_sdwa v44, v42, v183 dst_sel:DWORD dst_unused:UNUSED_PAD src0_sel:WORD_1 src1_sel:DWORD
	v_and_b32_sdwa v45, v40, v183 dst_sel:DWORD dst_unused:UNUSED_PAD src0_sel:WORD_1 src1_sel:DWORD
	v_add3_u32 v40, v40, v45, s37
	v_add3_u32 v42, v42, v44, s37
	v_and_b32_sdwa v44, v43, v183 dst_sel:DWORD dst_unused:UNUSED_PAD src0_sel:WORD_1 src1_sel:DWORD
	v_and_b32_sdwa v45, v41, v183 dst_sel:DWORD dst_unused:UNUSED_PAD src0_sel:WORD_1 src1_sel:DWORD
	v_add3_u32 v43, v43, v44, s37
	v_add3_u32 v41, v41, v45, s37
	v_and_b32_e32 v43, 0xffff0000, v43
	v_and_b32_e32 v44, 0xffff0000, v41
	v_or_b32_sdwa v41, v43, v42 dst_sel:DWORD dst_unused:UNUSED_PAD src0_sel:DWORD src1_sel:WORD_1
	v_or_b32_sdwa v40, v44, v40 dst_sel:DWORD dst_unused:UNUSED_PAD src0_sel:DWORD src1_sel:WORD_1
	global_store_dwordx2 v[52:53], v[40:41], off offset:64
	v_and_b32_sdwa v40, v38, v183 dst_sel:DWORD dst_unused:UNUSED_PAD src0_sel:WORD_1 src1_sel:DWORD
	v_and_b32_sdwa v41, v36, v183 dst_sel:DWORD dst_unused:UNUSED_PAD src0_sel:WORD_1 src1_sel:DWORD
	v_add3_u32 v36, v36, v41, s37
	v_add3_u32 v38, v38, v40, s37
	v_and_b32_sdwa v40, v39, v183 dst_sel:DWORD dst_unused:UNUSED_PAD src0_sel:WORD_1 src1_sel:DWORD
	v_and_b32_sdwa v41, v37, v183 dst_sel:DWORD dst_unused:UNUSED_PAD src0_sel:WORD_1 src1_sel:DWORD
	v_add3_u32 v39, v39, v40, s37
	v_add3_u32 v37, v37, v41, s37
	v_and_b32_e32 v39, 0xffff0000, v39
	v_and_b32_e32 v40, 0xffff0000, v37
	v_or_b32_sdwa v37, v39, v38 dst_sel:DWORD dst_unused:UNUSED_PAD src0_sel:DWORD src1_sel:WORD_1
	v_or_b32_sdwa v36, v40, v36 dst_sel:DWORD dst_unused:UNUSED_PAD src0_sel:DWORD src1_sel:WORD_1
	v_and_b32_sdwa v38, v34, v183 dst_sel:DWORD dst_unused:UNUSED_PAD src0_sel:WORD_1 src1_sel:DWORD
	v_and_b32_sdwa v39, v32, v183 dst_sel:DWORD dst_unused:UNUSED_PAD src0_sel:WORD_1 src1_sel:DWORD
	global_store_dwordx2 v[52:53], v[36:37], off offset:96
	v_or_b32_e32 v36, 0x60, v2
	v_add3_u32 v32, v32, v39, s37
	v_add3_u32 v34, v34, v38, s37
	v_and_b32_sdwa v38, v35, v183 dst_sel:DWORD dst_unused:UNUSED_PAD src0_sel:WORD_1 src1_sel:DWORD
	v_and_b32_sdwa v39, v33, v183 dst_sel:DWORD dst_unused:UNUSED_PAD src0_sel:WORD_1 src1_sel:DWORD
	v_mad_i64_i32 v[36:37], s[26:27], s14, v36, 0
	v_add3_u32 v35, v35, v38, s37
	v_add3_u32 v33, v33, v39, s37
	v_lshl_add_u64 v[36:37], v[36:37], 1, s[12:13]
	v_and_b32_e32 v35, 0xffff0000, v35
	v_and_b32_e32 v38, 0xffff0000, v33
	v_lshl_add_u64 v[36:37], v[36:37], 0, v[0:1]
	v_or_b32_sdwa v33, v35, v34 dst_sel:DWORD dst_unused:UNUSED_PAD src0_sel:DWORD src1_sel:WORD_1
	v_or_b32_sdwa v32, v38, v32 dst_sel:DWORD dst_unused:UNUSED_PAD src0_sel:DWORD src1_sel:WORD_1
	global_store_dwordx2 v[36:37], v[32:33], off
	v_and_b32_sdwa v32, v26, v183 dst_sel:DWORD dst_unused:UNUSED_PAD src0_sel:WORD_1 src1_sel:DWORD
	v_and_b32_sdwa v33, v24, v183 dst_sel:DWORD dst_unused:UNUSED_PAD src0_sel:WORD_1 src1_sel:DWORD
	v_add3_u32 v24, v24, v33, s37
	v_add3_u32 v26, v26, v32, s37
	v_and_b32_sdwa v32, v27, v183 dst_sel:DWORD dst_unused:UNUSED_PAD src0_sel:WORD_1 src1_sel:DWORD
	v_and_b32_sdwa v33, v25, v183 dst_sel:DWORD dst_unused:UNUSED_PAD src0_sel:WORD_1 src1_sel:DWORD
	v_add3_u32 v27, v27, v32, s37
	v_add3_u32 v25, v25, v33, s37
	v_and_b32_e32 v27, 0xffff0000, v27
	v_and_b32_e32 v32, 0xffff0000, v25
	v_or_b32_sdwa v25, v27, v26 dst_sel:DWORD dst_unused:UNUSED_PAD src0_sel:DWORD src1_sel:WORD_1
	v_or_b32_sdwa v24, v32, v24 dst_sel:DWORD dst_unused:UNUSED_PAD src0_sel:DWORD src1_sel:WORD_1
	global_store_dwordx2 v[36:37], v[24:25], off offset:32
	v_and_b32_sdwa v24, v22, v183 dst_sel:DWORD dst_unused:UNUSED_PAD src0_sel:WORD_1 src1_sel:DWORD
	v_and_b32_sdwa v25, v20, v183 dst_sel:DWORD dst_unused:UNUSED_PAD src0_sel:WORD_1 src1_sel:DWORD
	v_add3_u32 v20, v20, v25, s37
	v_add3_u32 v22, v22, v24, s37
	v_and_b32_sdwa v24, v23, v183 dst_sel:DWORD dst_unused:UNUSED_PAD src0_sel:WORD_1 src1_sel:DWORD
	v_and_b32_sdwa v25, v21, v183 dst_sel:DWORD dst_unused:UNUSED_PAD src0_sel:WORD_1 src1_sel:DWORD
	v_add3_u32 v23, v23, v24, s37
	v_add3_u32 v21, v21, v25, s37
	v_and_b32_e32 v23, 0xffff0000, v23
	v_and_b32_e32 v24, 0xffff0000, v21
; __device__ __forceinline__ unsigned pack2(float a, float b) { return (unsigned)f2bf(a) | ((unsigned)f2bf(b) << 16); }
; __device__ __forceinline__ void phase_gemm_in(const Params& p, char* smem) {
;     ...
; #pragma unroll
;     for (int i = 0; i < 8; ++i) {
;       const int m = mt * 256 + wm * 128 + i * 16 + (lane & 15);
; #pragma unroll
;       for (int j = 0; j < 4; ++j) {
;         const int n = ncol0 + wn * 64 + j * 16 + (lane >> 4) * 4;
;         uint2 o;
;         o.x = pack2(acc[i][j][0], acc[i][j][1]);
;         o.y = pack2(acc[i][j][2], acc[i][j][3]);
;         *(uint2*)(dst + (size_t)m * ldd + n) = o;
;       }
;     }
	v_or_b32_sdwa v21, v23, v22 dst_sel:DWORD dst_unused:UNUSED_PAD src0_sel:DWORD src1_sel:WORD_1
	v_or_b32_sdwa v20, v24, v20 dst_sel:DWORD dst_unused:UNUSED_PAD src0_sel:DWORD src1_sel:WORD_1
	global_store_dwordx2 v[36:37], v[20:21], off offset:64
	v_and_b32_sdwa v20, v18, v183 dst_sel:DWORD dst_unused:UNUSED_PAD src0_sel:WORD_1 src1_sel:DWORD
	v_and_b32_sdwa v21, v16, v183 dst_sel:DWORD dst_unused:UNUSED_PAD src0_sel:WORD_1 src1_sel:DWORD
	v_add3_u32 v16, v16, v21, s37
	v_add3_u32 v18, v18, v20, s37
	v_and_b32_sdwa v20, v19, v183 dst_sel:DWORD dst_unused:UNUSED_PAD src0_sel:WORD_1 src1_sel:DWORD
	v_and_b32_sdwa v21, v17, v183 dst_sel:DWORD dst_unused:UNUSED_PAD src0_sel:WORD_1 src1_sel:DWORD
	v_add3_u32 v19, v19, v20, s37
	v_add3_u32 v17, v17, v21, s37
	v_and_b32_e32 v19, 0xffff0000, v19
	v_and_b32_e32 v20, 0xffff0000, v17
	v_or_b32_sdwa v17, v19, v18 dst_sel:DWORD dst_unused:UNUSED_PAD src0_sel:DWORD src1_sel:WORD_1
	v_or_b32_sdwa v16, v20, v16 dst_sel:DWORD dst_unused:UNUSED_PAD src0_sel:DWORD src1_sel:WORD_1
	v_or_b32_e32 v2, 0x70, v2
	global_store_dwordx2 v[36:37], v[16:17], off offset:96
	v_mad_i64_i32 v[16:17], s[14:15], s14, v2, 0
	v_lshl_add_u64 v[16:17], v[16:17], 1, s[12:13]
	v_lshl_add_u64 v[0:1], v[16:17], 0, v[0:1]
	v_and_b32_sdwa v2, v14, v183 dst_sel:DWORD dst_unused:UNUSED_PAD src0_sel:WORD_1 src1_sel:DWORD
	v_and_b32_sdwa v16, v12, v183 dst_sel:DWORD dst_unused:UNUSED_PAD src0_sel:WORD_1 src1_sel:DWORD
	v_add3_u32 v12, v12, v16, s37
	v_add3_u32 v2, v14, v2, s37
	v_and_b32_sdwa v14, v15, v183 dst_sel:DWORD dst_unused:UNUSED_PAD src0_sel:WORD_1 src1_sel:DWORD
	v_and_b32_sdwa v16, v13, v183 dst_sel:DWORD dst_unused:UNUSED_PAD src0_sel:WORD_1 src1_sel:DWORD
	v_add3_u32 v14, v15, v14, s37
	v_add3_u32 v13, v13, v16, s37
	v_and_b32_e32 v14, 0xffff0000, v14
	v_and_b32_e32 v15, 0xffff0000, v13
	v_or_b32_sdwa v13, v14, v2 dst_sel:DWORD dst_unused:UNUSED_PAD src0_sel:DWORD src1_sel:WORD_1
	v_or_b32_sdwa v12, v15, v12 dst_sel:DWORD dst_unused:UNUSED_PAD src0_sel:DWORD src1_sel:WORD_1
	global_store_dwordx2 v[0:1], v[12:13], off
	v_and_b32_sdwa v2, v10, v183 dst_sel:DWORD dst_unused:UNUSED_PAD src0_sel:WORD_1 src1_sel:DWORD
	v_and_b32_sdwa v12, v8, v183 dst_sel:DWORD dst_unused:UNUSED_PAD src0_sel:WORD_1 src1_sel:DWORD
	v_add3_u32 v8, v8, v12, s37
	v_add3_u32 v2, v10, v2, s37
	v_and_b32_sdwa v10, v11, v183 dst_sel:DWORD dst_unused:UNUSED_PAD src0_sel:WORD_1 src1_sel:DWORD
	v_and_b32_sdwa v12, v9, v183 dst_sel:DWORD dst_unused:UNUSED_PAD src0_sel:WORD_1 src1_sel:DWORD
	v_add3_u32 v10, v11, v10, s37
	v_add3_u32 v9, v9, v12, s37
	v_and_b32_e32 v10, 0xffff0000, v10
	v_and_b32_e32 v11, 0xffff0000, v9
	v_or_b32_sdwa v9, v10, v2 dst_sel:DWORD dst_unused:UNUSED_PAD src0_sel:DWORD src1_sel:WORD_1
	v_or_b32_sdwa v8, v11, v8 dst_sel:DWORD dst_unused:UNUSED_PAD src0_sel:DWORD src1_sel:WORD_1
	global_store_dwordx2 v[0:1], v[8:9], off offset:32
	v_and_b32_sdwa v2, v6, v183 dst_sel:DWORD dst_unused:UNUSED_PAD src0_sel:WORD_1 src1_sel:DWORD
	v_and_b32_sdwa v8, v4, v183 dst_sel:DWORD dst_unused:UNUSED_PAD src0_sel:WORD_1 src1_sel:DWORD
	v_add3_u32 v4, v4, v8, s37
	v_add3_u32 v2, v6, v2, s37
	v_and_b32_sdwa v6, v7, v183 dst_sel:DWORD dst_unused:UNUSED_PAD src0_sel:WORD_1 src1_sel:DWORD
	v_and_b32_sdwa v8, v5, v183 dst_sel:DWORD dst_unused:UNUSED_PAD src0_sel:WORD_1 src1_sel:DWORD
	v_add3_u32 v6, v7, v6, s37
	v_add3_u32 v5, v5, v8, s37
	v_and_b32_e32 v6, 0xffff0000, v6
	v_and_b32_e32 v7, 0xffff0000, v5
	v_or_b32_sdwa v5, v6, v2 dst_sel:DWORD dst_unused:UNUSED_PAD src0_sel:DWORD src1_sel:WORD_1
	v_or_b32_sdwa v4, v7, v4 dst_sel:DWORD dst_unused:UNUSED_PAD src0_sel:DWORD src1_sel:WORD_1
	global_store_dwordx2 v[0:1], v[4:5], off offset:64
	v_and_b32_sdwa v5, v31, v183 dst_sel:DWORD dst_unused:UNUSED_PAD src0_sel:WORD_1 src1_sel:DWORD
	v_and_b32_sdwa v6, v29, v183 dst_sel:DWORD dst_unused:UNUSED_PAD src0_sel:WORD_1 src1_sel:DWORD
	v_and_b32_sdwa v2, v30, v183 dst_sel:DWORD dst_unused:UNUSED_PAD src0_sel:WORD_1 src1_sel:DWORD
	v_and_b32_sdwa v4, v28, v183 dst_sel:DWORD dst_unused:UNUSED_PAD src0_sel:WORD_1 src1_sel:DWORD
	v_add3_u32 v5, v31, v5, s37
	v_add3_u32 v6, v29, v6, s37
	s_add_i32 s23, s23, 1
	v_add3_u32 v4, v28, v4, s37
	v_add3_u32 v2, v30, v2, s37
	v_and_b32_e32 v5, 0xffff0000, v5
	v_and_b32_e32 v6, 0xffff0000, v6
	s_cmp_eq_u32 s23, s17
	v_or_b32_sdwa v5, v5, v2 dst_sel:DWORD dst_unused:UNUSED_PAD src0_sel:DWORD src1_sel:WORD_1
	v_or_b32_sdwa v4, v6, v4 dst_sel:DWORD dst_unused:UNUSED_PAD src0_sel:DWORD src1_sel:WORD_1
	s_cselect_b64 s[12:13], -1, 0
	s_mov_b32 s31, 0x18000
	global_store_dwordx2 v[0:1], v[4:5], off offset:96
	s_branch .LBB0_708
